# NSA selected-branch fast path: V address bases computed in the QK MFMA gaps
# speedup vs baseline: 1.0008x; 1.0008x over previous
.Lsel_fast2:
	v_add_u32_e32 v10, s91, v184
	ds_read_b128 v[2:5], v10
	v_add_u32_e32 v10, s91, v185
	ds_read_b128 v[208:211], v10
	v_add_u32_e32 v10, s91, v186
	ds_read_b128 v[212:215], v10
	v_add_u32_e32 v10, s91, v183
	ds_read_b128 v[216:219], v10
	s_waitcnt lgkmcnt(3)
	v_mfma_f32_32x32x16_bf16 v[80:95], v[2:5], v[140:143], 0
	v_add_u32_e32 v207, s91, v153
	v_add3_u32 v0, v207, v199, v178
	v_add_u32_e32 v10, s91, v182
	ds_read_b128 v[2:5], v10
	s_waitcnt lgkmcnt(3)
	v_mfma_f32_32x32x16_bf16 v[80:95], v[208:211], v[136:139], v[80:95]
	v_add_u32_e32 v6, s91, v200
	v_add3_u32 v6, v6, v178, v153
	v_add_u32_e32 v10, s91, v181
	ds_read_b128 v[208:211], v10
	s_waitcnt lgkmcnt(3)
	v_mfma_f32_32x32x16_bf16 v[80:95], v[212:215], v[132:135], v[80:95]
	v_add3_u32 v7, v207, v201, v178
	v_add_u32_e32 v230, s91, v202
	v_add_u32_e32 v10, s91, v180
	ds_read_b128 v[212:215], v10
	s_waitcnt lgkmcnt(3)
	v_mfma_f32_32x32x16_bf16 v[80:95], v[216:219], v[128:131], v[80:95]
	v_add3_u32 v230, v230, v178, v153
	v_add3_u32 v231, v207, v203, v178
	v_add_u32_e32 v10, s91, v179
	ds_read_b128 v[216:219], v10
	s_waitcnt lgkmcnt(3)
	v_mfma_f32_32x32x16_bf16 v[80:95], v[2:5], v[124:127], v[80:95]
	v_add_u32_e32 v241, s91, v204
	v_add3_u32 v241, v241, v178, v153
	v_add_u32_e32 v10, s91, v184
	ds_read_b128 v[2:5], v10 offset:8192
	s_waitcnt lgkmcnt(3)
	v_mfma_f32_32x32x16_bf16 v[80:95], v[208:211], v[120:123], v[80:95]
	v_add3_u32 v242, v207, v205, v178
	v_add_u32_e32 v243, s91, v206
	v_add_u32_e32 v10, s91, v185
	ds_read_b128 v[208:211], v10 offset:8192
	s_waitcnt lgkmcnt(3)
	v_mfma_f32_32x32x16_bf16 v[80:95], v[212:215], v[116:119], v[80:95]
	v_add3_u32 v243, v243, v178, v153
	v_add_u32_e32 v10, s91, v186
	ds_read_b128 v[212:215], v10 offset:8192
	s_waitcnt lgkmcnt(3)
	v_mfma_f32_32x32x16_bf16 v[80:95], v[216:219], v[112:115], v[80:95]
	v_add_u32_e32 v10, s91, v183
	ds_read_b128 v[216:219], v10 offset:8192
	s_waitcnt lgkmcnt(3)
	v_mfma_f32_32x32x16_bf16 v[96:111], v[2:5], v[140:143], 0
	v_add_u32_e32 v10, s91, v182
	ds_read_b128 v[2:5], v10 offset:8192
	s_waitcnt lgkmcnt(3)
	v_mfma_f32_32x32x16_bf16 v[96:111], v[208:211], v[136:139], v[96:111]
	v_add_u32_e32 v10, s91, v181
	ds_read_b128 v[208:211], v10 offset:8192
	s_waitcnt lgkmcnt(3)
	v_mfma_f32_32x32x16_bf16 v[96:111], v[212:215], v[132:135], v[96:111]
	v_add_u32_e32 v10, s91, v180
	ds_read_b128 v[212:215], v10 offset:8192
	s_waitcnt lgkmcnt(3)
	v_mfma_f32_32x32x16_bf16 v[96:111], v[216:219], v[128:131], v[96:111]
	v_add_u32_e32 v10, s91, v179
	ds_read_b128 v[216:219], v10 offset:8192
	v_exp_f32_e32 v80, v80
	v_exp_f32_e32 v81, v81
	v_exp_f32_e32 v82, v82
	s_waitcnt lgkmcnt(3)
	v_mfma_f32_32x32x16_bf16 v[96:111], v[2:5], v[124:127], v[96:111]
	v_exp_f32_e32 v83, v83
	v_exp_f32_e32 v84, v84
	v_exp_f32_e32 v85, v85
	s_waitcnt lgkmcnt(2)
	v_mfma_f32_32x32x16_bf16 v[96:111], v[208:211], v[120:123], v[96:111]
	v_exp_f32_e32 v86, v86
	v_exp_f32_e32 v87, v87
	v_exp_f32_e32 v88, v88
	s_waitcnt lgkmcnt(1)
	v_mfma_f32_32x32x16_bf16 v[96:111], v[212:215], v[116:119], v[96:111]
	v_exp_f32_e32 v89, v89
	v_exp_f32_e32 v90, v90
	v_exp_f32_e32 v91, v91
	s_waitcnt lgkmcnt(0)
	v_mfma_f32_32x32x16_bf16 v[96:111], v[216:219], v[112:115], v[96:111]
	v_exp_f32_e32 v92, v92
	v_exp_f32_e32 v93, v93
	v_exp_f32_e32 v94, v94
	v_exp_f32_e32 v95, v95
	ds_read_b64_tr_b16 v[12:13], v0 offset:32768
	ds_read_b64_tr_b16 v[14:15], v6 offset:34816
	ds_read_b64_tr_b16 v[208:209], v0 offset:36864
	ds_read_b64_tr_b16 v[210:211], v6 offset:38912
	ds_read_b64_tr_b16 v[212:213], v7 offset:32768
	ds_read_b64_tr_b16 v[214:215], v230 offset:34816
	ds_read_b64_tr_b16 v[216:217], v7 offset:36864
	ds_read_b64_tr_b16 v[218:219], v230 offset:38912
	s_nop 0
	v_pk_add_f32 v[244:245], v[80:81], v[82:83]
	v_pk_add_f32 v[246:247], v[84:85], v[86:87]
	v_pk_add_f32 v[232:233], v[88:89], v[90:91]
	v_pk_add_f32 v[234:235], v[92:93], v[94:95]
	v_pk_add_f32 v[244:245], v[244:245], v[246:247]
	v_pk_add_f32 v[232:233], v[232:233], v[234:235]
	v_pk_add_f32 v[244:245], v[244:245], v[232:233]
	v_add_f32_e32 v240, v244, v245
	v_cvt_pk_bf16_f32 v8, v80, v81
	v_cvt_pk_bf16_f32 v9, v82, v83
	v_cvt_pk_bf16_f32 v10, v84, v85
	v_cvt_pk_bf16_f32 v11, v86, v87
	v_cvt_pk_bf16_f32 v88, v88, v89
	v_cvt_pk_bf16_f32 v89, v90, v91
	v_cvt_pk_bf16_f32 v90, v92, v93
	v_cvt_pk_bf16_f32 v91, v94, v95
	v_cndmask_b32_e64 v8, 0, v8, s[72:73]
	v_cndmask_b32_e64 v9, 0, v9, s[72:73]
	v_cndmask_b32_e64 v10, 0, v10, s[72:73]
	v_cndmask_b32_e64 v11, 0, v11, s[72:73]
	v_cndmask_b32_e64 v88, 0, v88, s[72:73]
	v_cndmask_b32_e64 v89, 0, v89, s[72:73]
	v_cndmask_b32_e64 v90, 0, v90, s[72:73]
	v_cndmask_b32_e64 v91, 0, v91, s[72:73]
	ds_read_b64_tr_b16 v[80:81], v231 offset:32768
	ds_read_b64_tr_b16 v[82:83], v241 offset:34816
	ds_read_b64_tr_b16 v[84:85], v231 offset:36864
	ds_read_b64_tr_b16 v[86:87], v241 offset:38912
	ds_read_b64_tr_b16 v[92:93], v242 offset:32768
	ds_read_b64_tr_b16 v[94:95], v243 offset:34816
	ds_read_b64_tr_b16 v[236:237], v242 offset:36864
	ds_read_b64_tr_b16 v[238:239], v243 offset:38912
	s_waitcnt lgkmcnt(8)
	v_mfma_f32_32x32x16_bf16 v[64:79], v[8:11], v[12:15], v[64:79]
	v_exp_f32_e32 v96, v96
	v_exp_f32_e32 v97, v97
	v_mfma_f32_32x32x16_bf16 v[64:79], v[88:91], v[208:211], v[64:79]
	v_exp_f32_e32 v98, v98
	v_exp_f32_e32 v99, v99
	ds_read_b64_tr_b16 v[12:13], v0 offset:40960
	ds_read_b64_tr_b16 v[14:15], v6 offset:43008
	ds_read_b64_tr_b16 v[208:209], v0 offset:45056
	ds_read_b64_tr_b16 v[210:211], v6 offset:47104
	v_mfma_f32_32x32x16_bf16 v[48:63], v[8:11], v[212:215], v[48:63]
	v_exp_f32_e32 v100, v100
	v_exp_f32_e32 v101, v101
	v_mfma_f32_32x32x16_bf16 v[48:63], v[88:91], v[216:219], v[48:63]
	v_exp_f32_e32 v102, v102
	v_exp_f32_e32 v103, v103
	ds_read_b64_tr_b16 v[212:213], v7 offset:40960
	ds_read_b64_tr_b16 v[214:215], v230 offset:43008
	ds_read_b64_tr_b16 v[216:217], v7 offset:45056
	ds_read_b64_tr_b16 v[218:219], v230 offset:47104
	s_waitcnt lgkmcnt(8)
	v_mfma_f32_32x32x16_bf16 v[32:47], v[8:11], v[80:83], v[32:47]
	v_exp_f32_e32 v104, v104
	v_exp_f32_e32 v105, v105
	v_cvt_pk_bf16_f32 v2, v96, v97
	v_cvt_pk_bf16_f32 v3, v98, v99
	v_mfma_f32_32x32x16_bf16 v[32:47], v[88:91], v[84:87], v[32:47]
	v_exp_f32_e32 v106, v106
	v_exp_f32_e32 v107, v107
	v_cvt_pk_bf16_f32 v4, v100, v101
	v_cvt_pk_bf16_f32 v5, v102, v103
	ds_read_b64_tr_b16 v[80:81], v231 offset:40960
	ds_read_b64_tr_b16 v[82:83], v241 offset:43008
	ds_read_b64_tr_b16 v[84:85], v231 offset:45056
	ds_read_b64_tr_b16 v[86:87], v241 offset:47104
	v_mfma_f32_32x32x16_bf16 v[16:31], v[8:11], v[92:95], v[16:31]
	v_exp_f32_e32 v108, v108
	v_exp_f32_e32 v109, v109
	v_cndmask_b32_e64 v2, 0, v2, s[72:73]
	v_cndmask_b32_e64 v3, 0, v3, s[72:73]
	v_mfma_f32_32x32x16_bf16 v[16:31], v[88:91], v[236:239], v[16:31]
	v_exp_f32_e32 v110, v110
	v_exp_f32_e32 v111, v111
	v_cndmask_b32_e64 v4, 0, v4, s[72:73]
	v_cndmask_b32_e64 v5, 0, v5, s[72:73]
	ds_read_b64_tr_b16 v[92:93], v242 offset:40960
	ds_read_b64_tr_b16 v[94:95], v243 offset:43008
	ds_read_b64_tr_b16 v[236:237], v242 offset:45056
	ds_read_b64_tr_b16 v[238:239], v243 offset:47104
	s_waitcnt lgkmcnt(14)
	v_mfma_f32_32x32x16_bf16 v[64:79], v[2:5], v[12:15], v[64:79]
	v_pk_add_f32 v[244:245], v[96:97], v[98:99]
	v_pk_add_f32 v[246:247], v[100:101], v[102:103]
	v_pk_add_f32 v[6:7], v[104:105], v[106:107]
	v_pk_add_f32 v[230:231], v[108:109], v[110:111]
	s_waitcnt lgkmcnt(10)
	v_mfma_f32_32x32x16_bf16 v[48:63], v[2:5], v[212:215], v[48:63]
	v_pk_add_f32 v[244:245], v[244:245], v[246:247]
	v_pk_add_f32 v[6:7], v[6:7], v[230:231]
	v_pk_add_f32 v[244:245], v[244:245], v[6:7]
	v_add_f32_e32 v244, v244, v245
	s_waitcnt lgkmcnt(6)
	v_mfma_f32_32x32x16_bf16 v[32:47], v[2:5], v[80:83], v[32:47]
	v_cvt_pk_bf16_f32 v232, v104, v105
	v_cvt_pk_bf16_f32 v233, v106, v107
	v_cvt_pk_bf16_f32 v234, v108, v109
	v_cvt_pk_bf16_f32 v235, v110, v111
	s_waitcnt lgkmcnt(2)
	v_mfma_f32_32x32x16_bf16 v[16:31], v[2:5], v[92:95], v[16:31]
	v_cndmask_b32_e64 v232, 0, v232, s[72:73]
	v_cndmask_b32_e64 v233, 0, v233, s[72:73]
	v_cndmask_b32_e64 v234, 0, v234, s[72:73]
	v_cndmask_b32_e64 v235, 0, v235, s[72:73]
	v_add_f32_e32 v240, v240, v244
	v_cndmask_b32_e64 v240, 0, v240, s[72:73]
	v_add_f32_e32 v198, v198, v240
	s_waitcnt lgkmcnt(0)
	v_mfma_f32_32x32x16_bf16 v[64:79], v[232:235], v[208:211], v[64:79]
	v_mfma_f32_32x32x16_bf16 v[48:63], v[232:235], v[216:219], v[48:63]
	v_mfma_f32_32x32x16_bf16 v[32:47], v[232:235], v[84:87], v[32:47]
	v_mfma_f32_32x32x16_bf16 v[16:31], v[232:235], v[236:239], v[16:31]
	s_branch .LBB0_743
